# SGU queue item: all global loads of a loop iteration issued at its top (one round trip instead of ~29 per group), originals replaced by register moves
# baseline (speedup 1.0000x reference)
.LBB0_678:
	v_lshl_add_u64 v[8:9], v[4:5], 0, s[4:5]
	v_add_co_u32_e32 v8, vcc, 0x38c0000, v8
	s_add_u32 s4, s4, 0x100
	s_nop 0
	v_addc_co_u32_e32 v9, vcc, 0, v9, vcc
	global_load_dwordx4 v[82:85], v[8:9], off offset:1024
	global_load_dwordx4 v[86:89], v[8:9], off offset:1088
	global_load_dwordx4 v[90:93], v[8:9], off offset:1152
	global_load_dwordx4 v[94:97], v[8:9], off offset:1216
	s_waitcnt vmcnt(0)
	v_mov_b64_e32 v[10:11], v[82:83]
	v_mov_b64_e32 v[12:13], v[84:85]
	s_addc_u32 s5, s5, 0
	s_cmpk_eq_i32 s4, 0x400
	s_waitcnt lgkmcnt(0)
	v_and_b32_e32 v19, 0xffff0000, v11
	v_lshlrev_b32_e32 v16, 16, v11
	v_mul_f32_e32 v11, 0x3d372713, v19
	v_mul_f32_e32 v11, v11, v19
	v_fma_f32 v11, v11, v19, v19
	v_mul_f32_e32 v11, 0xbfcc422a, v11
	v_mul_f32_e32 v11, 0x3fb8aa3b, v11
	v_exp_f32_e32 v11, v11
	v_lshlrev_b32_e32 v21, 16, v12
	v_and_b32_e32 v23, 0xffff0000, v12
	v_lshlrev_b32_e32 v25, 16, v13
	v_add_f32_e32 v11, 1.0, v11
	v_rcp_f32_e32 v20, v11
	v_mul_f32_e32 v11, 0x3d372713, v21
	v_mul_f32_e32 v11, v11, v21
	v_fma_f32 v11, v11, v21, v21
	v_mul_f32_e32 v11, 0xbfcc422a, v11
	v_mul_f32_e32 v11, 0x3fb8aa3b, v11
	v_exp_f32_e32 v11, v11
	v_lshlrev_b32_e32 v3, 16, v10
	v_and_b32_e32 v10, 0xffff0000, v10
	v_mul_f32_e32 v14, 0x3d372713, v3
	v_add_f32_e32 v11, 1.0, v11
	v_rcp_f32_e32 v22, v11
	v_mul_f32_e32 v11, 0x3d372713, v23
	v_mul_f32_e32 v11, v11, v23
	v_fma_f32 v11, v11, v23, v23
	v_mul_f32_e32 v11, 0xbfcc422a, v11
	v_mul_f32_e32 v11, 0x3fb8aa3b, v11
	v_exp_f32_e32 v11, v11
	v_mul_f32_e32 v15, 0x3d372713, v10
	v_mul_f32_e32 v14, v14, v3
	v_mul_f32_e32 v15, v15, v10
	v_add_f32_e32 v11, 1.0, v11
	v_rcp_f32_e32 v24, v11
	v_mul_f32_e32 v11, 0x3d372713, v25
	v_mul_f32_e32 v11, v11, v25
	v_fma_f32 v11, v11, v25, v25
	v_mul_f32_e32 v11, 0xbfcc422a, v11
	v_mul_f32_e32 v11, 0x3fb8aa3b, v11
	v_exp_f32_e32 v11, v11
	v_fma_f32 v14, v14, v3, v3
	v_fma_f32 v15, v15, v10, v10
	v_mul_f32_e32 v14, 0xbfcc422a, v14
	v_mul_f32_e32 v15, 0xbfcc422a, v15
	v_mul_f32_e32 v18, 0x3d372713, v16
	v_add_f32_e32 v11, 1.0, v11
	v_and_b32_e32 v27, 0xffff0000, v13
	v_mul_f32_e32 v14, 0x3fb8aa3b, v14
	v_mul_f32_e32 v15, 0x3fb8aa3b, v15
	v_mul_f32_e32 v18, v18, v16
	v_rcp_f32_e32 v26, v11
	v_mul_f32_e32 v11, 0x3d372713, v27
	v_exp_f32_e32 v14, v14
	v_exp_f32_e32 v15, v15
	v_fma_f32 v18, v18, v16, v16
	v_mul_f32_e32 v11, v11, v27
	v_mul_f32_e32 v18, 0xbfcc422a, v18
	v_fma_f32 v11, v11, v27, v27
	v_mul_f32_e32 v18, 0x3fb8aa3b, v18
	v_mul_f32_e32 v11, 0xbfcc422a, v11
	v_exp_f32_e32 v18, v18
	v_mul_f32_e32 v11, 0x3fb8aa3b, v11
	v_add_f32_e32 v14, 1.0, v14
	v_add_f32_e32 v15, 1.0, v15
	v_exp_f32_e32 v11, v11
	v_rcp_f32_e32 v14, v14
	v_rcp_f32_e32 v15, v15
	v_add_f32_e32 v18, 1.0, v18
	v_rcp_f32_e32 v18, v18
	v_add_f32_e32 v11, 1.0, v11
	v_rcp_f32_e32 v28, v11
	v_mul_f32_e32 v11, v14, v3
	v_mul_f32_e32 v13, v15, v10
	v_mul_f32_e32 v10, v11, v11
	v_mul_f32_e32 v12, v13, v13
	v_pk_add_f32 v[10:11], v[10:11], v[12:13]
	v_mul_f32_e32 v13, v20, v19
	v_pk_add_f32 v[6:7], v[6:7], v[10:11]
	v_mul_f32_e32 v11, v18, v16
	v_mul_f32_e32 v10, v11, v11
	v_mul_f32_e32 v12, v13, v13
	v_pk_add_f32 v[10:11], v[10:11], v[12:13]
	v_mul_f32_e32 v13, v24, v23
	v_pk_add_f32 v[6:7], v[10:11], v[6:7]
	v_mul_f32_e32 v11, v22, v21
	v_mul_f32_e32 v10, v11, v11
	v_mul_f32_e32 v12, v13, v13
	v_pk_add_f32 v[10:11], v[10:11], v[12:13]
	v_mul_f32_e32 v13, v28, v27
	v_pk_add_f32 v[6:7], v[10:11], v[6:7]
	v_mul_f32_e32 v11, v26, v25
	v_mul_f32_e32 v10, v11, v11
	v_mul_f32_e32 v12, v13, v13
	v_pk_add_f32 v[10:11], v[10:11], v[12:13]
	s_nop 0
	v_pk_add_f32 v[6:7], v[10:11], v[6:7]
	v_mov_b64_e32 v[10:11], v[86:87]
	v_mov_b64_e32 v[12:13], v[88:89]
	s_waitcnt lgkmcnt(0)
	v_and_b32_e32 v19, 0xffff0000, v11
	v_lshlrev_b32_e32 v16, 16, v11
	v_mul_f32_e32 v11, 0x3d372713, v19
	v_mul_f32_e32 v11, v11, v19
	v_fma_f32 v11, v11, v19, v19
	v_mul_f32_e32 v11, 0xbfcc422a, v11
	v_mul_f32_e32 v11, 0x3fb8aa3b, v11
	v_exp_f32_e32 v11, v11
	v_lshlrev_b32_e32 v21, 16, v12
	v_and_b32_e32 v23, 0xffff0000, v12
	v_lshlrev_b32_e32 v25, 16, v13
	v_add_f32_e32 v11, 1.0, v11
	v_rcp_f32_e32 v20, v11
	v_mul_f32_e32 v11, 0x3d372713, v21
	v_mul_f32_e32 v11, v11, v21
	v_fma_f32 v11, v11, v21, v21
	v_mul_f32_e32 v11, 0xbfcc422a, v11
	v_mul_f32_e32 v11, 0x3fb8aa3b, v11
	v_exp_f32_e32 v11, v11
	v_lshlrev_b32_e32 v3, 16, v10
	v_and_b32_e32 v10, 0xffff0000, v10
	v_mul_f32_e32 v14, 0x3d372713, v3
	v_add_f32_e32 v11, 1.0, v11
	v_rcp_f32_e32 v22, v11
	v_mul_f32_e32 v11, 0x3d372713, v23
	v_mul_f32_e32 v11, v11, v23
	v_fma_f32 v11, v11, v23, v23
	v_mul_f32_e32 v11, 0xbfcc422a, v11
	v_mul_f32_e32 v11, 0x3fb8aa3b, v11
	v_exp_f32_e32 v11, v11
	v_mul_f32_e32 v15, 0x3d372713, v10
	v_mul_f32_e32 v14, v14, v3
	v_mul_f32_e32 v15, v15, v10
	v_add_f32_e32 v11, 1.0, v11
	v_rcp_f32_e32 v24, v11
	v_mul_f32_e32 v11, 0x3d372713, v25
	v_mul_f32_e32 v11, v11, v25
	v_fma_f32 v11, v11, v25, v25
	v_mul_f32_e32 v11, 0xbfcc422a, v11
	v_mul_f32_e32 v11, 0x3fb8aa3b, v11
	v_exp_f32_e32 v11, v11
	v_fma_f32 v14, v14, v3, v3
	v_fma_f32 v15, v15, v10, v10
	v_mul_f32_e32 v14, 0xbfcc422a, v14
	v_mul_f32_e32 v15, 0xbfcc422a, v15
	v_mul_f32_e32 v18, 0x3d372713, v16
	v_add_f32_e32 v11, 1.0, v11
	v_and_b32_e32 v27, 0xffff0000, v13
	v_mul_f32_e32 v14, 0x3fb8aa3b, v14
	v_mul_f32_e32 v15, 0x3fb8aa3b, v15
	v_mul_f32_e32 v18, v18, v16
	v_rcp_f32_e32 v26, v11
	v_mul_f32_e32 v11, 0x3d372713, v27
	v_exp_f32_e32 v14, v14
	v_exp_f32_e32 v15, v15
	v_fma_f32 v18, v18, v16, v16
	v_mul_f32_e32 v11, v11, v27
	v_mul_f32_e32 v18, 0xbfcc422a, v18
	v_fma_f32 v11, v11, v27, v27
	v_mul_f32_e32 v18, 0x3fb8aa3b, v18
	v_mul_f32_e32 v11, 0xbfcc422a, v11
	v_exp_f32_e32 v18, v18
	v_mul_f32_e32 v11, 0x3fb8aa3b, v11
	v_add_f32_e32 v14, 1.0, v14
	v_add_f32_e32 v15, 1.0, v15
	v_exp_f32_e32 v11, v11
	v_rcp_f32_e32 v14, v14
	v_rcp_f32_e32 v15, v15
	v_add_f32_e32 v18, 1.0, v18
	v_rcp_f32_e32 v18, v18
	v_add_f32_e32 v11, 1.0, v11
	v_rcp_f32_e32 v28, v11
	v_mul_f32_e32 v11, v14, v3
	v_mul_f32_e32 v13, v15, v10
	v_mul_f32_e32 v10, v11, v11
	v_mul_f32_e32 v12, v13, v13
	v_pk_add_f32 v[10:11], v[10:11], v[12:13]
	v_mul_f32_e32 v13, v20, v19
	v_pk_add_f32 v[6:7], v[6:7], v[10:11]
	v_mul_f32_e32 v11, v18, v16
	v_mul_f32_e32 v10, v11, v11
	v_mul_f32_e32 v12, v13, v13
	v_pk_add_f32 v[10:11], v[10:11], v[12:13]
	v_mul_f32_e32 v13, v24, v23
	v_pk_add_f32 v[6:7], v[10:11], v[6:7]
	v_mul_f32_e32 v11, v22, v21
	v_mul_f32_e32 v10, v11, v11
	v_mul_f32_e32 v12, v13, v13
	v_pk_add_f32 v[10:11], v[10:11], v[12:13]
	v_mul_f32_e32 v13, v28, v27
	v_pk_add_f32 v[6:7], v[10:11], v[6:7]
	v_mul_f32_e32 v11, v26, v25
	v_mul_f32_e32 v10, v11, v11
	v_mul_f32_e32 v12, v13, v13
	v_pk_add_f32 v[10:11], v[10:11], v[12:13]
	s_nop 0
	v_pk_add_f32 v[6:7], v[10:11], v[6:7]
	v_mov_b64_e32 v[10:11], v[90:91]
	v_mov_b64_e32 v[12:13], v[92:93]
	s_waitcnt lgkmcnt(0)
	v_and_b32_e32 v19, 0xffff0000, v11
	v_lshlrev_b32_e32 v16, 16, v11
	v_mul_f32_e32 v11, 0x3d372713, v19
	v_mul_f32_e32 v11, v11, v19
	v_fma_f32 v11, v11, v19, v19
	v_mul_f32_e32 v11, 0xbfcc422a, v11
	v_mul_f32_e32 v11, 0x3fb8aa3b, v11
	v_exp_f32_e32 v11, v11
	v_lshlrev_b32_e32 v21, 16, v12
	v_and_b32_e32 v23, 0xffff0000, v12
	v_lshlrev_b32_e32 v25, 16, v13
	v_add_f32_e32 v11, 1.0, v11
	v_rcp_f32_e32 v20, v11
	v_mul_f32_e32 v11, 0x3d372713, v21
	v_mul_f32_e32 v11, v11, v21
	v_fma_f32 v11, v11, v21, v21
	v_mul_f32_e32 v11, 0xbfcc422a, v11
	v_mul_f32_e32 v11, 0x3fb8aa3b, v11
	v_exp_f32_e32 v11, v11
	v_lshlrev_b32_e32 v3, 16, v10
	v_and_b32_e32 v10, 0xffff0000, v10
	v_mul_f32_e32 v14, 0x3d372713, v3
	v_add_f32_e32 v11, 1.0, v11
	v_rcp_f32_e32 v22, v11
	v_mul_f32_e32 v11, 0x3d372713, v23
	v_mul_f32_e32 v11, v11, v23
	v_fma_f32 v11, v11, v23, v23
	v_mul_f32_e32 v11, 0xbfcc422a, v11
	v_mul_f32_e32 v11, 0x3fb8aa3b, v11
	v_exp_f32_e32 v11, v11
	v_mul_f32_e32 v15, 0x3d372713, v10
	v_mul_f32_e32 v14, v14, v3
	v_mul_f32_e32 v15, v15, v10
	v_add_f32_e32 v11, 1.0, v11
	v_rcp_f32_e32 v24, v11
	v_mul_f32_e32 v11, 0x3d372713, v25
	v_mul_f32_e32 v11, v11, v25
	v_fma_f32 v11, v11, v25, v25
	v_mul_f32_e32 v11, 0xbfcc422a, v11
	v_mul_f32_e32 v11, 0x3fb8aa3b, v11
	v_exp_f32_e32 v11, v11
	v_fma_f32 v14, v14, v3, v3
	v_fma_f32 v15, v15, v10, v10
	v_mul_f32_e32 v14, 0xbfcc422a, v14
	v_mul_f32_e32 v15, 0xbfcc422a, v15
	v_mul_f32_e32 v18, 0x3d372713, v16
	v_add_f32_e32 v11, 1.0, v11
	v_and_b32_e32 v27, 0xffff0000, v13
	v_mul_f32_e32 v14, 0x3fb8aa3b, v14
	v_mul_f32_e32 v15, 0x3fb8aa3b, v15
	v_mul_f32_e32 v18, v18, v16
	v_rcp_f32_e32 v26, v11
	v_mul_f32_e32 v11, 0x3d372713, v27
	v_exp_f32_e32 v14, v14
	v_exp_f32_e32 v15, v15
	v_fma_f32 v18, v18, v16, v16
	v_mul_f32_e32 v11, v11, v27
	v_mul_f32_e32 v18, 0xbfcc422a, v18
	v_fma_f32 v11, v11, v27, v27
	v_mul_f32_e32 v18, 0x3fb8aa3b, v18
	v_mul_f32_e32 v11, 0xbfcc422a, v11
	v_exp_f32_e32 v18, v18
	v_mul_f32_e32 v11, 0x3fb8aa3b, v11
	v_add_f32_e32 v14, 1.0, v14
	v_add_f32_e32 v15, 1.0, v15
	v_exp_f32_e32 v11, v11
	v_rcp_f32_e32 v14, v14
	v_rcp_f32_e32 v15, v15
	v_add_f32_e32 v18, 1.0, v18
	v_rcp_f32_e32 v18, v18
	v_add_f32_e32 v11, 1.0, v11
	v_rcp_f32_e32 v28, v11
	v_mul_f32_e32 v11, v14, v3
	v_mul_f32_e32 v13, v15, v10
	v_mul_f32_e32 v10, v11, v11
	v_mul_f32_e32 v12, v13, v13
	v_pk_add_f32 v[10:11], v[10:11], v[12:13]
	v_mul_f32_e32 v13, v20, v19
	v_pk_add_f32 v[6:7], v[6:7], v[10:11]
	v_mul_f32_e32 v11, v18, v16
	v_mul_f32_e32 v10, v11, v11
	v_mul_f32_e32 v12, v13, v13
	v_pk_add_f32 v[10:11], v[10:11], v[12:13]
	v_mul_f32_e32 v13, v24, v23
	v_pk_add_f32 v[6:7], v[10:11], v[6:7]
	v_mul_f32_e32 v11, v22, v21
	v_mul_f32_e32 v10, v11, v11
	v_mul_f32_e32 v12, v13, v13
	v_pk_add_f32 v[10:11], v[10:11], v[12:13]
	v_mul_f32_e32 v13, v28, v27
	v_pk_add_f32 v[6:7], v[10:11], v[6:7]
	v_mul_f32_e32 v11, v26, v25
	v_mul_f32_e32 v10, v11, v11
	v_mul_f32_e32 v12, v13, v13
	v_pk_add_f32 v[10:11], v[10:11], v[12:13]
	s_nop 0
	v_pk_add_f32 v[10:11], v[10:11], v[6:7]
	v_mov_b64_e32 v[6:7], v[94:95]
	v_mov_b64_e32 v[8:9], v[96:97]
	s_waitcnt lgkmcnt(0)
	v_and_b32_e32 v16, 0xffff0000, v7
	v_lshlrev_b32_e32 v14, 16, v7
	v_mul_f32_e32 v7, 0x3d372713, v16
	v_mul_f32_e32 v7, v7, v16
	v_fma_f32 v7, v7, v16, v16
	v_mul_f32_e32 v7, 0xbfcc422a, v7
	v_mul_f32_e32 v7, 0x3fb8aa3b, v7
	v_exp_f32_e32 v7, v7
	v_lshlrev_b32_e32 v19, 16, v8
	v_and_b32_e32 v21, 0xffff0000, v8
	v_lshlrev_b32_e32 v23, 16, v9
	v_add_f32_e32 v7, 1.0, v7
	v_rcp_f32_e32 v18, v7
	v_mul_f32_e32 v7, 0x3d372713, v19
	v_mul_f32_e32 v7, v7, v19
	v_fma_f32 v7, v7, v19, v19
	v_mul_f32_e32 v7, 0xbfcc422a, v7
	v_mul_f32_e32 v7, 0x3fb8aa3b, v7
	v_exp_f32_e32 v7, v7
	v_lshlrev_b32_e32 v3, 16, v6
	v_and_b32_e32 v6, 0xffff0000, v6
	v_mul_f32_e32 v12, 0x3d372713, v3
	v_add_f32_e32 v7, 1.0, v7
	v_rcp_f32_e32 v20, v7
	v_mul_f32_e32 v7, 0x3d372713, v21
	v_mul_f32_e32 v7, v7, v21
	v_fma_f32 v7, v7, v21, v21
	v_mul_f32_e32 v7, 0xbfcc422a, v7
	v_mul_f32_e32 v7, 0x3fb8aa3b, v7
	v_exp_f32_e32 v7, v7
	v_mul_f32_e32 v13, 0x3d372713, v6
	v_mul_f32_e32 v12, v12, v3
	v_mul_f32_e32 v13, v13, v6
	v_add_f32_e32 v7, 1.0, v7
	v_rcp_f32_e32 v22, v7
	v_mul_f32_e32 v7, 0x3d372713, v23
	v_mul_f32_e32 v7, v7, v23
	v_fma_f32 v7, v7, v23, v23
	v_mul_f32_e32 v7, 0xbfcc422a, v7
	v_mul_f32_e32 v7, 0x3fb8aa3b, v7
	v_exp_f32_e32 v7, v7
	v_fma_f32 v12, v12, v3, v3
	v_fma_f32 v13, v13, v6, v6
	v_mul_f32_e32 v12, 0xbfcc422a, v12
	v_mul_f32_e32 v13, 0xbfcc422a, v13
	v_mul_f32_e32 v15, 0x3d372713, v14
	v_add_f32_e32 v7, 1.0, v7
	v_and_b32_e32 v25, 0xffff0000, v9
	v_mul_f32_e32 v12, 0x3fb8aa3b, v12
	v_mul_f32_e32 v13, 0x3fb8aa3b, v13
	v_mul_f32_e32 v15, v15, v14
	v_rcp_f32_e32 v24, v7
	v_mul_f32_e32 v7, 0x3d372713, v25
	v_exp_f32_e32 v12, v12
	v_exp_f32_e32 v13, v13
	v_fma_f32 v15, v15, v14, v14
	v_mul_f32_e32 v7, v7, v25
	v_mul_f32_e32 v15, 0xbfcc422a, v15
	v_fma_f32 v7, v7, v25, v25
	v_mul_f32_e32 v15, 0x3fb8aa3b, v15
	v_mul_f32_e32 v7, 0xbfcc422a, v7
	v_exp_f32_e32 v15, v15
	v_mul_f32_e32 v7, 0x3fb8aa3b, v7
	v_add_f32_e32 v12, 1.0, v12
	v_add_f32_e32 v13, 1.0, v13
	v_exp_f32_e32 v7, v7
	v_rcp_f32_e32 v12, v12
	v_rcp_f32_e32 v13, v13
	v_add_f32_e32 v15, 1.0, v15
	v_rcp_f32_e32 v15, v15
	v_add_f32_e32 v7, 1.0, v7
	v_rcp_f32_e32 v26, v7
	v_mul_f32_e32 v7, v12, v3
	v_mul_f32_e32 v9, v13, v6
	v_mul_f32_e32 v6, v7, v7
	v_mul_f32_e32 v8, v9, v9
	v_pk_add_f32 v[6:7], v[6:7], v[8:9]
	v_mul_f32_e32 v9, v15, v14
	v_pk_add_f32 v[6:7], v[10:11], v[6:7]
	v_mul_f32_e32 v11, v18, v16
	v_mul_f32_e32 v8, v9, v9
	v_mul_f32_e32 v10, v11, v11
	v_pk_add_f32 v[8:9], v[8:9], v[10:11]
	v_mul_f32_e32 v11, v22, v21
	v_pk_add_f32 v[6:7], v[8:9], v[6:7]
	v_mul_f32_e32 v9, v20, v19
	v_mul_f32_e32 v8, v9, v9
	v_mul_f32_e32 v10, v11, v11
	v_pk_add_f32 v[8:9], v[8:9], v[10:11]
	v_mul_f32_e32 v11, v26, v25
	v_pk_add_f32 v[6:7], v[8:9], v[6:7]
	v_mul_f32_e32 v9, v24, v23
	v_mul_f32_e32 v8, v9, v9
	v_mul_f32_e32 v10, v11, v11
	v_pk_add_f32 v[8:9], v[8:9], v[10:11]
	s_nop 0
	v_pk_add_f32 v[6:7], v[8:9], v[6:7]
	s_cbranch_scc0 .LBB0_678
	v_and_b32_e32 v4, 64, v234
	v_xor_b32_e32 v3, 1, v234
	v_add_u32_e32 v8, 64, v4
	v_cmp_lt_i32_e32 vcc, v3, v8
	s_mov_b32 s2, 0x3b000000
	v_lshlrev_b32_e32 v16, 5, v0
	v_cndmask_b32_e32 v3, v234, v3, vcc
	v_lshlrev_b32_e32 v3, 2, v3
	ds_bpermute_b32 v5, v3, v7
	ds_bpermute_b32 v4, v3, v6
	v_xor_b32_e32 v3, 2, v234
	v_cmp_lt_i32_e32 vcc, v3, v8
	v_cmp_lt_u32_e64 s[40:41], 1, v0
	v_lshl_add_u32 v8, v0, 6, 0
	v_cndmask_b32_e32 v3, v234, v3, vcc
	v_lshlrev_b32_e32 v3, 2, v3
	s_waitcnt lgkmcnt(0)
	v_pk_add_f32 v[4:5], v[6:7], v[4:5]
	ds_bpermute_b32 v7, v3, v5
	ds_bpermute_b32 v6, v3, v4
	v_mul_u32_u24_e32 v11, 0x880, v0
	s_mov_b64 s[42:43], 0
	s_mov_b64 s[90:91], s[44:45]
	s_mov_b64 s[14:15], 0x10000
	s_waitcnt lgkmcnt(0)
	v_pk_add_f32 v[4:5], v[4:5], v[6:7]
	v_bfe_u32 v6, v1, 4, 2
	v_pk_mul_f32 v[36:37], v[4:5], s[2:3] op_sel_hi:[1,0]
	v_lshl_add_u32 v7, v2, 1, 0
	v_fma_f32 v3, -v37, v37, v36
	v_max_f32_e32 v3, 0, v3
	v_add_f32_e32 v3, 0x358637bd, v3
	v_mul_f32_e32 v4, 0x4b800000, v3
	v_cmp_gt_f32_e32 vcc, s33, v3
	s_movk_i32 s2, 0x110
	v_lshlrev_b32_e32 v10, 3, v6
	v_cndmask_b32_e32 v3, v3, v4, vcc
	v_rsq_f32_e32 v3, v3
	v_lshl_add_u32 v6, v6, 4, 0
	v_mul_lo_u32 v9, v2, s2
	v_and_b32_e32 v5, 15, v1
	v_mul_f32_e32 v4, 0x45800000, v3
	v_cndmask_b32_e32 v36, v3, v4, vcc
	v_bfi_b32 v4, -16, v2, v1
	v_mad_u64_u32 v[38:39], s[4:5], v4, s2, v[6:7]
	v_readlane_b32 s4, v255, 37
	v_readlane_b32 s5, v255, 38
	v_ashrrev_i32_e32 v3, 31, v2
	v_cmp_gt_i32_e32 vcc, 64, v2
	v_lshl_add_u64 v[40:41], s[4:5], 0, v[16:17]
	v_readlane_b32 s4, v255, 39
	v_lshlrev_b64 v[2:3], 9, v[2:3]
	v_readlane_b32 s5, v255, 40
	v_lshl_or_b32 v1, v0, 3, 1
	v_lshlrev_b32_e32 v16, 7, v0
	v_lshl_add_u64 v[2:3], s[4:5], 0, v[2:3]
	v_readlane_b32 s4, v255, 41
	v_add_u32_e32 v0, s8, v4
	v_mul_u32_u24_e32 v12, 0x110, v1
	v_mul_u32_u24_e32 v13, 0x110, v5
	v_ashrrev_i32_e32 v5, 31, v4
	v_readlane_b32 s5, v255, 42
	v_ashrrev_i32_e32 v1, 31, v0
	v_lshlrev_b64 v[46:47], 10, v[0:1]
	v_lshl_add_u64 v[44:45], v[4:5], 2, s[4:5]
	v_mad_i64_i32 v[48:49], s[4:5], v0, s66, 0
	s_and_b64 s[40:41], vcc, s[40:41]
	v_lshl_add_u64 v[42:43], v[2:3], 0, v[16:17]
	v_or_b32_e32 v46, v46, v10
	v_or_b32_e32 v48, v48, v10
	v_add_u32_e32 v16, v7, v11
	v_add_u32_e32 v39, v7, v12
	v_add_u32_e32 v56, v8, v9
	v_add_u32_e32 v57, v6, v13
.LBB0_680:
	s_mov_b32 s4, 0
	s_ashr_i32 s5, s4, 31
	s_lshl_b64 s[4:5], s[4:5], 3
	v_lshl_add_u64 v[0:1], s[90:91], 0, v[34:35]
	s_add_u32 s4, s0, s4
	v_add_co_u32_e32 v6, vcc, s86, v0
	s_addc_u32 s5, s1, s5
	s_nop 0
	v_addc_co_u32_e32 v7, vcc, 0, v1, vcc
	s_load_dwordx2 s[4:5], s[4:5], 0x38
	s_load_dwordx2 s[98:99], s[0:1], 0x48
	s_load_dwordx2 s[100:101], s[0:1], 0x50
	s_mov_b32 s8, 0
	s_ashr_i32 s9, s8, 31
	s_lshl_b64 s[8:9], s[8:9], 3
	s_add_u32 s8, s0, s8
	s_addc_u32 s9, s1, s9
	s_load_dwordx2 s[8:9], s[8:9], 0x40
	s_mov_b32 s2, 0x190c0000
	s_waitcnt lgkmcnt(0)
	v_lshl_add_u64 v[70:71], s[4:5], 0, v[40:41]
	v_lshl_add_u64 v[72:73], s[8:9], 0, v[40:41]
	v_lshl_add_u64 v[70:71], v[70:71], 0, s[42:43]
	v_lshl_add_u64 v[72:73], v[72:73], 0, s[42:43]
	v_lshl_add_u64 v[74:75], s[98:99], 0, v[42:43]
	v_lshl_add_u64 v[76:77], s[100:101], 0, v[44:45]
	v_lshl_add_u64 v[194:195], s[90:91], 0, v[48:49]
	v_lshl_add_u64 v[76:77], v[76:77], 0, s[42:43]
	v_add_co_u32_e32 v194, vcc, s86, v194
	s_nop 1
	v_addc_co_u32_e32 v195, vcc, 0, v195, vcc
	global_load_dwordx4 v[82:85], v[6:7], off offset:1024
	global_load_dwordx4 v[130:133], v[72:73], off
	global_load_dwordx4 v[98:101], v[70:71], off
	global_load_dwordx4 v[102:105], v[70:71], off offset:16
	global_load_dwordx4 v[134:137], v[72:73], off offset:16
	global_load_dwordx4 v[86:89], v[6:7], off offset:1088
	global_load_dwordx4 v[106:109], v[70:71], off offset:128
	global_load_dwordx4 v[138:141], v[72:73], off offset:128
	global_load_dwordx4 v[110:113], v[70:71], off offset:144
	global_load_dwordx4 v[142:145], v[72:73], off offset:144
	global_load_dwordx4 v[90:93], v[6:7], off offset:1152
	global_load_dwordx4 v[114:117], v[70:71], off offset:256
	global_load_dwordx4 v[146:149], v[72:73], off offset:256
	global_load_dwordx4 v[118:121], v[70:71], off offset:272
	global_load_dwordx4 v[150:153], v[72:73], off offset:272
	global_load_dwordx4 v[94:97], v[6:7], off offset:1216
	global_load_dwordx4 v[122:125], v[70:71], off offset:384
	global_load_dwordx4 v[154:157], v[72:73], off offset:384
	global_load_dwordx4 v[126:129], v[70:71], off offset:400
	global_load_dwordx4 v[158:161], v[72:73], off offset:400
	global_load_dwordx4 v[162:165], v[74:75], off offset:-64
	global_load_dwordx4 v[166:169], v[74:75], off offset:-48
	global_load_dwordx4 v[170:173], v[74:75], off offset:-32
	global_load_dwordx4 v[174:177], v[74:75], off offset:-16
	global_load_dwordx4 v[178:181], v[74:75], off
	global_load_dwordx4 v[182:185], v[74:75], off offset:16
	global_load_dwordx4 v[186:189], v[74:75], off offset:32
	global_load_dwordx4 v[190:193], v[74:75], off offset:48
	global_load_dword v224, v[76:77], off
	global_load_dwordx2 v[208:209], v[194:195], off
	global_load_dwordx2 v[210:211], v[194:195], off offset:32
	global_load_dwordx2 v[212:213], v[194:195], off offset:64
	global_load_dwordx2 v[214:215], v[194:195], off offset:96
	global_load_dwordx2 v[216:217], v[194:195], off offset:128
	global_load_dwordx2 v[218:219], v[194:195], off offset:160
	global_load_dwordx2 v[220:221], v[194:195], off offset:192
	global_load_dwordx2 v[222:223], v[194:195], off offset:224
	s_waitcnt vmcnt(0)
	v_mov_b64_e32 v[0:1], v[82:83]
	v_mov_b64_e32 v[2:3], v[84:85]
	v_lshl_add_u64 v[8:9], s[8:9], 0, v[40:41]
	v_lshl_add_u64 v[8:9], v[8:9], 0, s[42:43]
	v_mov_b64_e32 v[18:19], v[130:131]
	v_mov_b64_e32 v[20:21], v[132:133]
	v_lshlrev_b32_e32 v4, 16, v0
	v_mul_f32_e32 v5, 0x3d372713, v4
	v_mul_f32_e32 v5, v5, v4
	v_fma_f32 v5, v5, v4, v4
	v_mul_f32_e32 v5, 0xbfcc422a, v5
	v_mul_f32_e32 v5, 0x3fb8aa3b, v5
	v_exp_f32_e32 v5, v5
	v_and_b32_e32 v0, 0xffff0000, v0
	v_add_f32_e32 v5, 1.0, v5
	v_rcp_f32_e32 v5, v5
	s_nop 0
	v_fma_f32 v4, v5, v4, -v37
	v_mul_f32_e32 v14, v36, v4
	v_lshl_add_u64 v[4:5], s[4:5], 0, v[40:41]
	v_lshl_add_u64 v[4:5], v[4:5], 0, s[42:43]
	v_mov_b64_e32 v[10:11], v[98:99]
	v_mov_b64_e32 v[12:13], v[100:101]
	v_fma_f32 v10, v10, v14, v18
	v_cvt_pk_bf16_f32 v10, v10, v17
	ds_write_b16 v16, v10 offset:34816
	v_mul_f32_e32 v10, 0x3d372713, v0
	v_mul_f32_e32 v10, v10, v0
	v_fma_f32 v10, v10, v0, v0
	v_mul_f32_e32 v10, 0xbfcc422a, v10
	v_mul_f32_e32 v10, 0x3fb8aa3b, v10
	v_exp_f32_e32 v10, v10
	s_nop 0
	v_add_f32_e32 v10, 1.0, v10
	v_rcp_f32_e32 v10, v10
	s_nop 0
	v_fma_f32 v0, v10, v0, -v37
	v_mul_f32_e32 v0, v36, v0
	v_fma_f32 v0, v11, v0, v19
	v_cvt_pk_bf16_f32 v0, v0, v17
	ds_write_b16 v39, v0 offset:34816
	v_lshlrev_b32_e32 v0, 16, v1
	v_mul_f32_e32 v10, 0x3d372713, v0
	v_mul_f32_e32 v10, v10, v0
	v_fma_f32 v10, v10, v0, v0
	v_mul_f32_e32 v10, 0xbfcc422a, v10
	v_mul_f32_e32 v10, 0x3fb8aa3b, v10
	v_exp_f32_e32 v10, v10
	s_nop 0
	v_add_f32_e32 v10, 1.0, v10
	v_rcp_f32_e32 v10, v10
	s_nop 0
	v_fma_f32 v0, v10, v0, -v37
	v_mul_f32_e32 v0, v36, v0
	v_fma_f32 v0, v12, v0, v20
	v_cvt_pk_bf16_f32 v0, v0, v17
	ds_write_b16 v39, v0 offset:35088
	v_and_b32_e32 v0, 0xffff0000, v1
	v_mul_f32_e32 v1, 0x3d372713, v0
	v_mul_f32_e32 v1, v1, v0
	v_fma_f32 v1, v1, v0, v0
	v_mul_f32_e32 v1, 0xbfcc422a, v1
	v_mul_f32_e32 v1, 0x3fb8aa3b, v1
	v_exp_f32_e32 v1, v1
	s_nop 0
	v_add_f32_e32 v1, 1.0, v1
	v_rcp_f32_e32 v1, v1
	s_nop 0
	v_fma_f32 v0, v1, v0, -v37
	v_mul_f32_e32 v0, v36, v0
	v_fmac_f32_e32 v21, v13, v0
	v_cvt_pk_bf16_f32 v0, v21, v17
	ds_write_b16 v39, v0 offset:35360
	v_mov_b64_e32 v[10:11], v[102:103]
	v_mov_b64_e32 v[12:13], v[104:105]
	v_mov_b64_e32 v[18:19], v[134:135]
	v_mov_b64_e32 v[20:21], v[136:137]
	v_lshlrev_b32_e32 v0, 16, v2
	v_mul_f32_e32 v1, 0x3d372713, v0
	v_mul_f32_e32 v1, v1, v0
	v_fma_f32 v1, v1, v0, v0
	v_mul_f32_e32 v1, 0xbfcc422a, v1
	v_mul_f32_e32 v1, 0x3fb8aa3b, v1
	v_exp_f32_e32 v1, v1
	s_nop 0
	v_add_f32_e32 v1, 1.0, v1
	v_rcp_f32_e32 v1, v1
	s_nop 0
	v_fma_f32 v0, v1, v0, -v37
	v_mul_f32_e32 v0, v36, v0
	s_waitcnt vmcnt(0)
	v_fma_f32 v0, v0, v10, v18
	v_cvt_pk_bf16_f32 v0, v0, v17
	ds_write_b16 v39, v0 offset:35632
	v_and_b32_e32 v0, 0xffff0000, v2
	v_mul_f32_e32 v1, 0x3d372713, v0
	v_mul_f32_e32 v1, v1, v0
	v_fma_f32 v1, v1, v0, v0
	v_mul_f32_e32 v1, 0xbfcc422a, v1
	v_mul_f32_e32 v1, 0x3fb8aa3b, v1
	v_exp_f32_e32 v1, v1
	s_nop 0
	v_add_f32_e32 v1, 1.0, v1
	v_rcp_f32_e32 v1, v1
	s_nop 0
	v_fma_f32 v0, v1, v0, -v37
	v_mul_f32_e32 v0, v36, v0
	v_fma_f32 v0, v0, v11, v19
	v_cvt_pk_bf16_f32 v0, v0, v17
	ds_write_b16 v39, v0 offset:35904
	v_lshlrev_b32_e32 v0, 16, v3
	v_mul_f32_e32 v1, 0x3d372713, v0
	v_mul_f32_e32 v1, v1, v0
	v_fma_f32 v1, v1, v0, v0
	v_mul_f32_e32 v1, 0xbfcc422a, v1
	v_mul_f32_e32 v1, 0x3fb8aa3b, v1
	v_exp_f32_e32 v1, v1
	s_nop 0
	v_add_f32_e32 v1, 1.0, v1
	v_rcp_f32_e32 v1, v1
	s_nop 0
	v_fma_f32 v0, v1, v0, -v37
	v_mul_f32_e32 v0, v36, v0
	v_fma_f32 v0, v0, v12, v20
	v_cvt_pk_bf16_f32 v0, v0, v17
	ds_write_b16 v39, v0 offset:36176
	v_and_b32_e32 v0, 0xffff0000, v3
	v_mul_f32_e32 v1, 0x3d372713, v0
	v_mul_f32_e32 v1, v1, v0
	v_fma_f32 v1, v1, v0, v0
	v_mul_f32_e32 v1, 0xbfcc422a, v1
	v_mul_f32_e32 v1, 0x3fb8aa3b, v1
	v_exp_f32_e32 v1, v1
	s_nop 0
	v_add_f32_e32 v1, 1.0, v1
	v_rcp_f32_e32 v1, v1
	s_nop 0
	v_fma_f32 v0, v1, v0, -v37
	v_mul_f32_e32 v0, v36, v0
	v_fmac_f32_e32 v21, v0, v13
	v_cvt_pk_bf16_f32 v0, v21, v17
	ds_write_b16 v39, v0 offset:36448
	v_mov_b64_e32 v[0:1], v[86:87]
	v_mov_b64_e32 v[2:3], v[88:89]
	s_waitcnt lgkmcnt(0)
	v_lshlrev_b32_e32 v10, 16, v0
	v_mul_f32_e32 v11, 0x3d372713, v10
	v_mul_f32_e32 v11, v11, v10
	v_fma_f32 v11, v11, v10, v10
	v_mul_f32_e32 v11, 0xbfcc422a, v11
	v_mul_f32_e32 v11, 0x3fb8aa3b, v11
	v_exp_f32_e32 v11, v11
	v_and_b32_e32 v0, 0xffff0000, v0
	v_add_f32_e32 v11, 1.0, v11
	v_rcp_f32_e32 v11, v11
	s_nop 0
	v_fma_f32 v10, v11, v10, -v37
	v_mul_f32_e32 v14, v36, v10
	v_mov_b64_e32 v[10:11], v[106:107]
	v_mov_b64_e32 v[12:13], v[108:109]
	v_mov_b64_e32 v[18:19], v[138:139]
	v_mov_b64_e32 v[20:21], v[140:141]
	v_fma_f32 v10, v10, v14, v18
	v_cvt_pk_bf16_f32 v10, v10, v17
	ds_write_b16 v39, v10 offset:43248
	v_mul_f32_e32 v10, 0x3d372713, v0
	v_mul_f32_e32 v10, v10, v0
	v_fma_f32 v10, v10, v0, v0
	v_mul_f32_e32 v10, 0xbfcc422a, v10
	v_mul_f32_e32 v10, 0x3fb8aa3b, v10
	v_exp_f32_e32 v10, v10
	s_nop 0
	v_add_f32_e32 v10, 1.0, v10
	v_rcp_f32_e32 v10, v10
	s_nop 0
	v_fma_f32 v0, v10, v0, -v37
	v_mul_f32_e32 v0, v36, v0
	v_fma_f32 v0, v11, v0, v19
	v_cvt_pk_bf16_f32 v0, v0, v17
	ds_write_b16 v39, v0 offset:43520
	v_lshlrev_b32_e32 v0, 16, v1
	v_mul_f32_e32 v10, 0x3d372713, v0
	v_mul_f32_e32 v10, v10, v0
	v_fma_f32 v10, v10, v0, v0
	v_mul_f32_e32 v10, 0xbfcc422a, v10
	v_mul_f32_e32 v10, 0x3fb8aa3b, v10
	v_exp_f32_e32 v10, v10
	s_nop 0
	v_add_f32_e32 v10, 1.0, v10
	v_rcp_f32_e32 v10, v10
	s_nop 0
	v_fma_f32 v0, v10, v0, -v37
	v_mul_f32_e32 v0, v36, v0
	v_fma_f32 v0, v12, v0, v20
	v_cvt_pk_bf16_f32 v0, v0, v17
	ds_write_b16 v39, v0 offset:43792
	v_and_b32_e32 v0, 0xffff0000, v1
	v_mul_f32_e32 v1, 0x3d372713, v0
	v_mul_f32_e32 v1, v1, v0
	v_fma_f32 v1, v1, v0, v0
	v_mul_f32_e32 v1, 0xbfcc422a, v1
	v_mul_f32_e32 v1, 0x3fb8aa3b, v1
	v_exp_f32_e32 v1, v1
	s_nop 0
	v_add_f32_e32 v1, 1.0, v1
	v_rcp_f32_e32 v1, v1
	s_nop 0
	v_fma_f32 v0, v1, v0, -v37
	v_mul_f32_e32 v0, v36, v0
	v_fmac_f32_e32 v21, v13, v0
	v_cvt_pk_bf16_f32 v0, v21, v17
	ds_write_b16 v39, v0 offset:44064
	v_mov_b64_e32 v[10:11], v[110:111]
	v_mov_b64_e32 v[12:13], v[112:113]
	v_mov_b64_e32 v[18:19], v[142:143]
	v_mov_b64_e32 v[20:21], v[144:145]
	v_lshlrev_b32_e32 v0, 16, v2
	v_mul_f32_e32 v1, 0x3d372713, v0
	v_mul_f32_e32 v1, v1, v0
	v_fma_f32 v1, v1, v0, v0
	v_mul_f32_e32 v1, 0xbfcc422a, v1
	v_mul_f32_e32 v1, 0x3fb8aa3b, v1
	v_exp_f32_e32 v1, v1
	s_nop 0
	v_add_f32_e32 v1, 1.0, v1
	v_rcp_f32_e32 v1, v1
	s_nop 0
	v_fma_f32 v0, v1, v0, -v37
	v_mul_f32_e32 v0, v36, v0
	s_waitcnt vmcnt(0)
	v_fma_f32 v0, v0, v10, v18
	v_cvt_pk_bf16_f32 v0, v0, v17
	ds_write_b16 v39, v0 offset:44336
	v_and_b32_e32 v0, 0xffff0000, v2
	v_mul_f32_e32 v1, 0x3d372713, v0
	v_mul_f32_e32 v1, v1, v0
	v_fma_f32 v1, v1, v0, v0
	v_mul_f32_e32 v1, 0xbfcc422a, v1
	v_mul_f32_e32 v1, 0x3fb8aa3b, v1
	v_exp_f32_e32 v1, v1
	s_nop 0
	v_add_f32_e32 v1, 1.0, v1
	v_rcp_f32_e32 v1, v1
	s_nop 0
	v_fma_f32 v0, v1, v0, -v37
	v_mul_f32_e32 v0, v36, v0
	v_fma_f32 v0, v0, v11, v19
	v_cvt_pk_bf16_f32 v0, v0, v17
	ds_write_b16 v39, v0 offset:44608
	v_lshlrev_b32_e32 v0, 16, v3
	v_mul_f32_e32 v1, 0x3d372713, v0
	v_mul_f32_e32 v1, v1, v0
	v_fma_f32 v1, v1, v0, v0
	v_mul_f32_e32 v1, 0xbfcc422a, v1
	v_mul_f32_e32 v1, 0x3fb8aa3b, v1
	v_exp_f32_e32 v1, v1
	s_nop 0
	v_add_f32_e32 v1, 1.0, v1
	v_rcp_f32_e32 v1, v1
	s_nop 0
	v_fma_f32 v0, v1, v0, -v37
	v_mul_f32_e32 v0, v36, v0
	v_fma_f32 v0, v0, v12, v20
	v_cvt_pk_bf16_f32 v0, v0, v17
	ds_write_b16 v39, v0 offset:44880
	v_and_b32_e32 v0, 0xffff0000, v3
	v_mul_f32_e32 v1, 0x3d372713, v0
	v_mul_f32_e32 v1, v1, v0
	v_fma_f32 v1, v1, v0, v0
	v_mul_f32_e32 v1, 0xbfcc422a, v1
	v_mul_f32_e32 v1, 0x3fb8aa3b, v1
	v_exp_f32_e32 v1, v1
	s_nop 0
	v_add_f32_e32 v1, 1.0, v1
	v_rcp_f32_e32 v1, v1
	s_nop 0
	v_fma_f32 v0, v1, v0, -v37
	v_mul_f32_e32 v0, v36, v0
	v_fmac_f32_e32 v21, v0, v13
	v_cvt_pk_bf16_f32 v0, v21, v17
	ds_write_b16 v39, v0 offset:45152
	v_mov_b64_e32 v[0:1], v[90:91]
	v_mov_b64_e32 v[2:3], v[92:93]
	s_waitcnt lgkmcnt(0)
	v_lshlrev_b32_e32 v10, 16, v0
	v_mul_f32_e32 v11, 0x3d372713, v10
	v_mul_f32_e32 v11, v11, v10
	v_fma_f32 v11, v11, v10, v10
	v_mul_f32_e32 v11, 0xbfcc422a, v11
	v_mul_f32_e32 v11, 0x3fb8aa3b, v11
	v_exp_f32_e32 v11, v11
	v_and_b32_e32 v0, 0xffff0000, v0
	v_add_f32_e32 v11, 1.0, v11
	v_rcp_f32_e32 v11, v11
	s_nop 0
	v_fma_f32 v10, v11, v10, -v37
	v_mul_f32_e32 v14, v36, v10
	v_mov_b64_e32 v[10:11], v[114:115]
	v_mov_b64_e32 v[12:13], v[116:117]
	v_mov_b64_e32 v[18:19], v[146:147]
	v_mov_b64_e32 v[20:21], v[148:149]
	v_fma_f32 v10, v10, v14, v18
	v_cvt_pk_bf16_f32 v10, v10, v17
	ds_write_b16 v39, v10 offset:51952
	v_mul_f32_e32 v10, 0x3d372713, v0
	v_mul_f32_e32 v10, v10, v0
	v_fma_f32 v10, v10, v0, v0
	v_mul_f32_e32 v10, 0xbfcc422a, v10
	v_mul_f32_e32 v10, 0x3fb8aa3b, v10
	v_exp_f32_e32 v10, v10
	s_nop 0
	v_add_f32_e32 v10, 1.0, v10
	v_rcp_f32_e32 v10, v10
	s_nop 0
	v_fma_f32 v0, v10, v0, -v37
	v_mul_f32_e32 v0, v36, v0
	v_fma_f32 v0, v11, v0, v19
	v_cvt_pk_bf16_f32 v0, v0, v17
	ds_write_b16 v39, v0 offset:52224
	v_lshlrev_b32_e32 v0, 16, v1
	v_mul_f32_e32 v10, 0x3d372713, v0
	v_mul_f32_e32 v10, v10, v0
	v_fma_f32 v10, v10, v0, v0
	v_mul_f32_e32 v10, 0xbfcc422a, v10
	v_mul_f32_e32 v10, 0x3fb8aa3b, v10
	v_exp_f32_e32 v10, v10
	s_nop 0
	v_add_f32_e32 v10, 1.0, v10
	v_rcp_f32_e32 v10, v10
	s_nop 0
	v_fma_f32 v0, v10, v0, -v37
	v_mul_f32_e32 v0, v36, v0
	v_fma_f32 v0, v12, v0, v20
	v_cvt_pk_bf16_f32 v0, v0, v17
	ds_write_b16 v39, v0 offset:52496
	v_and_b32_e32 v0, 0xffff0000, v1
	v_mul_f32_e32 v1, 0x3d372713, v0
	v_mul_f32_e32 v1, v1, v0
	v_fma_f32 v1, v1, v0, v0
	v_mul_f32_e32 v1, 0xbfcc422a, v1
	v_mul_f32_e32 v1, 0x3fb8aa3b, v1
	v_exp_f32_e32 v1, v1
	s_nop 0
	v_add_f32_e32 v1, 1.0, v1
	v_rcp_f32_e32 v1, v1
	s_nop 0
	v_fma_f32 v0, v1, v0, -v37
	v_mul_f32_e32 v0, v36, v0
	v_fmac_f32_e32 v21, v13, v0
	v_cvt_pk_bf16_f32 v0, v21, v17
	ds_write_b16 v39, v0 offset:52768
	v_mov_b64_e32 v[10:11], v[118:119]
	v_mov_b64_e32 v[12:13], v[120:121]
	v_mov_b64_e32 v[18:19], v[150:151]
	v_mov_b64_e32 v[20:21], v[152:153]
	v_lshlrev_b32_e32 v0, 16, v2
	v_mul_f32_e32 v1, 0x3d372713, v0
	v_mul_f32_e32 v1, v1, v0
	v_fma_f32 v1, v1, v0, v0
	v_mul_f32_e32 v1, 0xbfcc422a, v1
	v_mul_f32_e32 v1, 0x3fb8aa3b, v1
	v_exp_f32_e32 v1, v1
	s_nop 0
	v_add_f32_e32 v1, 1.0, v1
	v_rcp_f32_e32 v1, v1
	s_nop 0
	v_fma_f32 v0, v1, v0, -v37
	v_mul_f32_e32 v0, v36, v0
	s_waitcnt vmcnt(0)
	v_fma_f32 v0, v0, v10, v18
	v_cvt_pk_bf16_f32 v0, v0, v17
	ds_write_b16 v39, v0 offset:53040
	v_and_b32_e32 v0, 0xffff0000, v2
	v_mul_f32_e32 v1, 0x3d372713, v0
	v_mul_f32_e32 v1, v1, v0
	v_fma_f32 v1, v1, v0, v0
	v_mul_f32_e32 v1, 0xbfcc422a, v1
	v_mul_f32_e32 v1, 0x3fb8aa3b, v1
	v_exp_f32_e32 v1, v1
	s_nop 0
	v_add_f32_e32 v1, 1.0, v1
	v_rcp_f32_e32 v1, v1
	s_nop 0
	v_fma_f32 v0, v1, v0, -v37
	v_mul_f32_e32 v0, v36, v0
	v_fma_f32 v0, v0, v11, v19
	v_cvt_pk_bf16_f32 v0, v0, v17
	ds_write_b16 v39, v0 offset:53312
	v_lshlrev_b32_e32 v0, 16, v3
	v_mul_f32_e32 v1, 0x3d372713, v0
	v_mul_f32_e32 v1, v1, v0
	v_fma_f32 v1, v1, v0, v0
	v_mul_f32_e32 v1, 0xbfcc422a, v1
	v_mul_f32_e32 v1, 0x3fb8aa3b, v1
	v_exp_f32_e32 v1, v1
	s_nop 0
	v_add_f32_e32 v1, 1.0, v1
	v_rcp_f32_e32 v1, v1
	s_nop 0
	v_fma_f32 v0, v1, v0, -v37
	v_mul_f32_e32 v0, v36, v0
	v_fma_f32 v0, v0, v12, v20
	v_cvt_pk_bf16_f32 v0, v0, v17
	ds_write_b16 v39, v0 offset:53584
	v_and_b32_e32 v0, 0xffff0000, v3
	v_mul_f32_e32 v1, 0x3d372713, v0
	v_mul_f32_e32 v1, v1, v0
	v_fma_f32 v1, v1, v0, v0
	v_mul_f32_e32 v1, 0xbfcc422a, v1
	v_mul_f32_e32 v1, 0x3fb8aa3b, v1
	v_exp_f32_e32 v1, v1
	s_nop 0
	v_add_f32_e32 v1, 1.0, v1
	v_rcp_f32_e32 v1, v1
	s_nop 0
	v_fma_f32 v0, v1, v0, -v37
	v_mul_f32_e32 v0, v36, v0
	v_fmac_f32_e32 v21, v0, v13
	v_cvt_pk_bf16_f32 v0, v21, v17
	ds_write_b16 v39, v0 offset:53856
	v_mov_b64_e32 v[0:1], v[94:95]
	v_mov_b64_e32 v[2:3], v[96:97]
	v_mov_b64_e32 v[10:11], v[122:123]
	v_mov_b64_e32 v[12:13], v[124:125]
	v_mov_b64_e32 v[18:19], v[154:155]
	v_mov_b64_e32 v[20:21], v[156:157]
	s_waitcnt lgkmcnt(0)
	v_lshlrev_b32_e32 v6, 16, v0
	v_mul_f32_e32 v7, 0x3d372713, v6
	v_mul_f32_e32 v7, v7, v6
	v_fma_f32 v7, v7, v6, v6
	v_mul_f32_e32 v7, 0xbfcc422a, v7
	v_mul_f32_e32 v7, 0x3fb8aa3b, v7
	v_exp_f32_e32 v7, v7
	v_and_b32_e32 v0, 0xffff0000, v0
	v_add_f32_e32 v7, 1.0, v7
	v_rcp_f32_e32 v7, v7
	s_nop 0
	v_fma_f32 v6, v7, v6, -v37
	v_mul_f32_e32 v6, v36, v6
	v_fma_f32 v6, v10, v6, v18
	v_cvt_pk_bf16_f32 v6, v6, v17
	ds_write_b16 v39, v6 offset:60656
	v_mul_f32_e32 v6, 0x3d372713, v0
	v_mul_f32_e32 v6, v6, v0
	v_fma_f32 v6, v6, v0, v0
	v_mul_f32_e32 v6, 0xbfcc422a, v6
	v_mul_f32_e32 v6, 0x3fb8aa3b, v6
	v_exp_f32_e32 v6, v6
	s_nop 0
	v_add_f32_e32 v6, 1.0, v6
	v_rcp_f32_e32 v6, v6
	s_nop 0
	v_fma_f32 v0, v6, v0, -v37
	v_mul_f32_e32 v0, v36, v0
	v_fma_f32 v0, v11, v0, v19
	v_cvt_pk_bf16_f32 v0, v0, v17
	ds_write_b16 v39, v0 offset:60928
	v_lshlrev_b32_e32 v0, 16, v1
	v_mul_f32_e32 v6, 0x3d372713, v0
	v_mul_f32_e32 v6, v6, v0
	v_fma_f32 v6, v6, v0, v0
	v_mul_f32_e32 v6, 0xbfcc422a, v6
	v_mul_f32_e32 v6, 0x3fb8aa3b, v6
	v_exp_f32_e32 v6, v6
	s_nop 0
	v_add_f32_e32 v6, 1.0, v6
	v_rcp_f32_e32 v6, v6
	s_nop 0
	v_fma_f32 v0, v6, v0, -v37
	v_mul_f32_e32 v0, v36, v0
	v_fma_f32 v0, v12, v0, v20
	v_cvt_pk_bf16_f32 v0, v0, v17
	ds_write_b16 v39, v0 offset:61200
	v_and_b32_e32 v0, 0xffff0000, v1
	v_mul_f32_e32 v1, 0x3d372713, v0
	v_mul_f32_e32 v1, v1, v0
	v_fma_f32 v1, v1, v0, v0
	v_mul_f32_e32 v1, 0xbfcc422a, v1
	v_mul_f32_e32 v1, 0x3fb8aa3b, v1
	v_exp_f32_e32 v1, v1
	s_nop 0
	v_add_f32_e32 v1, 1.0, v1
	v_rcp_f32_e32 v1, v1
	s_nop 0
	v_fma_f32 v0, v1, v0, -v37
	v_mul_f32_e32 v0, v36, v0
	v_fmac_f32_e32 v21, v13, v0
	v_cvt_pk_bf16_f32 v0, v21, v17
	ds_write_b16 v39, v0 offset:61472
	v_mov_b64_e32 v[4:5], v[126:127]
	v_mov_b64_e32 v[6:7], v[128:129]
	s_nop 0
	v_mov_b64_e32 v[8:9], v[158:159]
	v_mov_b64_e32 v[10:11], v[160:161]
	v_lshlrev_b32_e32 v0, 16, v2
	v_mul_f32_e32 v1, 0x3d372713, v0
	v_mul_f32_e32 v1, v1, v0
	v_fma_f32 v1, v1, v0, v0
	v_mul_f32_e32 v1, 0xbfcc422a, v1
	v_mul_f32_e32 v1, 0x3fb8aa3b, v1
	v_exp_f32_e32 v1, v1
	s_nop 0
	v_add_f32_e32 v1, 1.0, v1
	v_rcp_f32_e32 v1, v1
	s_nop 0
	v_fma_f32 v0, v1, v0, -v37
	v_mul_f32_e32 v0, v36, v0
	s_waitcnt vmcnt(0)
	v_fma_f32 v0, v0, v4, v8
	v_cvt_pk_bf16_f32 v0, v0, v17
	ds_write_b16 v39, v0 offset:61744
	v_and_b32_e32 v0, 0xffff0000, v2
	v_mul_f32_e32 v1, 0x3d372713, v0
	v_mul_f32_e32 v1, v1, v0
	v_fma_f32 v1, v1, v0, v0
	v_mul_f32_e32 v1, 0xbfcc422a, v1
	v_mul_f32_e32 v1, 0x3fb8aa3b, v1
	v_exp_f32_e32 v1, v1
	s_nop 0
	v_add_f32_e32 v1, 1.0, v1
	v_rcp_f32_e32 v1, v1
	s_nop 0
	v_fma_f32 v0, v1, v0, -v37
	v_mul_f32_e32 v0, v36, v0
	v_fma_f32 v0, v0, v5, v9
	v_cvt_pk_bf16_f32 v0, v0, v17
	ds_write_b16 v39, v0 offset:62016
	v_lshlrev_b32_e32 v0, 16, v3
	v_mul_f32_e32 v1, 0x3d372713, v0
	v_mul_f32_e32 v1, v1, v0
	v_fma_f32 v1, v1, v0, v0
	v_mul_f32_e32 v1, 0xbfcc422a, v1
	v_mul_f32_e32 v1, 0x3fb8aa3b, v1
	v_exp_f32_e32 v1, v1
	s_nop 0
	v_add_f32_e32 v1, 1.0, v1
	v_rcp_f32_e32 v1, v1
	s_nop 0
	v_fma_f32 v0, v1, v0, -v37
	v_mul_f32_e32 v0, v36, v0
	v_fma_f32 v0, v0, v6, v10
	v_cvt_pk_bf16_f32 v0, v0, v17
	ds_write_b16 v39, v0 offset:62288
	v_and_b32_e32 v0, 0xffff0000, v3
	v_mul_f32_e32 v1, 0x3d372713, v0
	v_mul_f32_e32 v1, v1, v0
	v_fma_f32 v1, v1, v0, v0
	v_mul_f32_e32 v1, 0xbfcc422a, v1
	v_mul_f32_e32 v1, 0x3fb8aa3b, v1
	v_exp_f32_e32 v1, v1
	s_nop 0
	v_add_f32_e32 v1, 1.0, v1
	v_rcp_f32_e32 v1, v1
	s_nop 0
	v_fma_f32 v0, v1, v0, -v37
	v_mul_f32_e32 v0, v36, v0
	v_fmac_f32_e32 v11, v0, v7
	v_cvt_pk_bf16_f32 v0, v11, v17
	ds_write_b16 v39, v0 offset:62560
	s_mov_b32 s4, 0
	s_ashr_i32 s5, s4, 31
	s_lshl_b64 s[4:5], s[4:5], 3
	s_add_u32 s4, s0, s4
	s_addc_u32 s5, s1, s5
	s_load_dwordx2 s[4:5], s[4:5], 0x48
	s_waitcnt lgkmcnt(0)
	v_lshl_add_u64 v[4:5], s[4:5], 0, v[42:43]
	v_mov_b64_e32 v[0:1], v[162:163]
	v_mov_b64_e32 v[2:3], v[164:165]
	v_lshl_add_u64 v[42:43], v[42:43], 0, s[14:15]
	v_cndmask_b32_e64 v2, v2, 0, s[40:41]
	v_cndmask_b32_e64 v3, v3, 0, s[40:41]
	v_cndmask_b32_e64 v0, v0, 0, s[40:41]
	v_cndmask_b32_e64 v1, v1, 0, s[40:41]
	v_cvt_pk_bf16_f32 v6, v0, v1
	v_cvt_pk_bf16_f32 v7, v2, v3
	v_mov_b64_e32 v[0:1], v[166:167]
	v_mov_b64_e32 v[2:3], v[168:169]
	v_cndmask_b32_e64 v0, v0, 0, s[40:41]
	v_cndmask_b32_e64 v1, v1, 0, s[40:41]
	v_cndmask_b32_e64 v2, v2, 0, s[40:41]
	v_cndmask_b32_e64 v3, v3, 0, s[40:41]
	v_cvt_pk_bf16_f32 v0, v0, v1
	v_cvt_pk_bf16_f32 v1, v2, v3
	ds_write2_b64 v56, v[6:7], v[0:1] offset1:1
	v_mov_b64_e32 v[0:1], v[170:171]
	v_mov_b64_e32 v[2:3], v[172:173]
	v_cndmask_b32_e64 v2, v2, 0, s[40:41]
	v_cndmask_b32_e64 v3, v3, 0, s[40:41]
	v_cndmask_b32_e64 v0, v0, 0, s[40:41]
	v_cndmask_b32_e64 v1, v1, 0, s[40:41]
	v_cvt_pk_bf16_f32 v6, v0, v1
	v_cvt_pk_bf16_f32 v7, v2, v3
	v_mov_b64_e32 v[0:1], v[174:175]
	v_mov_b64_e32 v[2:3], v[176:177]
	v_cndmask_b32_e64 v0, v0, 0, s[40:41]
	v_cndmask_b32_e64 v1, v1, 0, s[40:41]
	v_cndmask_b32_e64 v2, v2, 0, s[40:41]
	v_cndmask_b32_e64 v3, v3, 0, s[40:41]
	v_cvt_pk_bf16_f32 v0, v0, v1
	v_cvt_pk_bf16_f32 v1, v2, v3
	ds_write2_b64 v56, v[6:7], v[0:1] offset0:2 offset1:3
	v_mov_b64_e32 v[0:1], v[178:179]
	v_mov_b64_e32 v[2:3], v[180:181]
	v_cndmask_b32_e64 v2, v2, 0, s[40:41]
	v_cndmask_b32_e64 v3, v3, 0, s[40:41]
	v_cndmask_b32_e64 v0, v0, 0, s[40:41]
	v_cndmask_b32_e64 v1, v1, 0, s[40:41]
	v_cvt_pk_bf16_f32 v6, v0, v1
	v_cvt_pk_bf16_f32 v7, v2, v3
	v_mov_b64_e32 v[0:1], v[182:183]
	v_mov_b64_e32 v[2:3], v[184:185]
	v_cndmask_b32_e64 v0, v0, 0, s[40:41]
	v_cndmask_b32_e64 v1, v1, 0, s[40:41]
	v_cndmask_b32_e64 v2, v2, 0, s[40:41]
	v_cndmask_b32_e64 v3, v3, 0, s[40:41]
	v_cvt_pk_bf16_f32 v0, v0, v1
	v_cvt_pk_bf16_f32 v1, v2, v3
	ds_write2_b64 v56, v[6:7], v[0:1] offset0:4 offset1:5
	v_mov_b64_e32 v[0:1], v[186:187]
	v_mov_b64_e32 v[2:3], v[188:189]
	v_cndmask_b32_e64 v2, v2, 0, s[40:41]
	v_cndmask_b32_e64 v3, v3, 0, s[40:41]
	v_cndmask_b32_e64 v0, v0, 0, s[40:41]
	v_cndmask_b32_e64 v1, v1, 0, s[40:41]
	v_cvt_pk_bf16_f32 v6, v0, v1
	v_cvt_pk_bf16_f32 v7, v2, v3
	v_mov_b64_e32 v[0:1], v[190:191]
	v_mov_b64_e32 v[2:3], v[192:193]
	v_cndmask_b32_e64 v0, v0, 0, s[40:41]
	v_cndmask_b32_e64 v1, v1, 0, s[40:41]
	v_cndmask_b32_e64 v2, v2, 0, s[40:41]
	v_cndmask_b32_e64 v3, v3, 0, s[40:41]
	v_cvt_pk_bf16_f32 v0, v0, v1
	v_cvt_pk_bf16_f32 v1, v2, v3
	ds_write2_b64 v56, v[6:7], v[0:1] offset0:6 offset1:7
	s_waitcnt lgkmcnt(0)
	s_barrier
	ds_read_b128 v[0:3], v38
	ds_read_b128 v[4:7], v57 offset:34816
	ds_read_b128 v[8:11], v57 offset:39168
	ds_read_b128 v[12:15], v57 offset:43520
	ds_read_b128 v[18:21], v57 offset:47872
	ds_read_b128 v[22:25], v57 offset:52224
	ds_read_b128 v[26:29], v57 offset:56576
	ds_read_b128 v[30:33], v57 offset:60928
	ds_read_b128 v[50:53], v57 offset:65280
	s_waitcnt lgkmcnt(7)
	v_mfma_f32_16x16x32_bf16 v[4:7], v[4:7], v[0:3], 0
	s_waitcnt lgkmcnt(6)
	v_mfma_f32_16x16x32_bf16 v[8:11], v[8:11], v[0:3], 0
	s_waitcnt lgkmcnt(5)
	v_mfma_f32_16x16x32_bf16 v[12:15], v[12:15], v[0:3], 0
	s_waitcnt lgkmcnt(4)
	v_mfma_f32_16x16x32_bf16 v[18:21], v[18:21], v[0:3], 0
	s_waitcnt lgkmcnt(3)
	v_mfma_f32_16x16x32_bf16 v[22:25], v[22:25], v[0:3], 0
	s_waitcnt lgkmcnt(2)
	v_mfma_f32_16x16x32_bf16 v[26:29], v[26:29], v[0:3], 0
	s_waitcnt lgkmcnt(1)
	v_mfma_f32_16x16x32_bf16 v[30:33], v[30:33], v[0:3], 0
	s_waitcnt lgkmcnt(0)
	v_mfma_f32_16x16x32_bf16 v[0:3], v[50:53], v[0:3], 0
	ds_read_b128 v[50:53], v38 offset:64
	ds_read_b128 v[58:61], v57 offset:34880
	s_waitcnt lgkmcnt(0)
	v_mfma_f32_16x16x32_bf16 v[4:7], v[58:61], v[50:53], v[4:7]
	ds_read_b128 v[58:61], v57 offset:39232
	s_waitcnt lgkmcnt(0)
	v_mfma_f32_16x16x32_bf16 v[8:11], v[58:61], v[50:53], v[8:11]
	ds_read_b128 v[58:61], v57 offset:43584
	s_waitcnt lgkmcnt(0)
	v_mfma_f32_16x16x32_bf16 v[12:15], v[58:61], v[50:53], v[12:15]
	ds_read_b128 v[58:61], v57 offset:47936
	s_waitcnt lgkmcnt(0)
	v_mfma_f32_16x16x32_bf16 v[18:21], v[58:61], v[50:53], v[18:21]
	ds_read_b128 v[58:61], v57 offset:52288
	s_waitcnt lgkmcnt(0)
	v_mfma_f32_16x16x32_bf16 v[22:25], v[58:61], v[50:53], v[22:25]
	ds_read_b128 v[58:61], v57 offset:56640
	s_waitcnt lgkmcnt(0)
	v_mfma_f32_16x16x32_bf16 v[26:29], v[58:61], v[50:53], v[26:29]
	ds_read_b128 v[58:61], v57 offset:60992
	s_waitcnt lgkmcnt(0)
	v_mfma_f32_16x16x32_bf16 v[30:33], v[58:61], v[50:53], v[30:33]
	ds_read_b128 v[58:61], v57 offset:65344
	s_waitcnt lgkmcnt(0)
	v_mfma_f32_16x16x32_bf16 v[0:3], v[58:61], v[50:53], v[0:3]
	ds_read_b128 v[50:53], v38 offset:128
	ds_read_b128 v[58:61], v57 offset:34944
	s_waitcnt lgkmcnt(0)
	v_mfma_f32_16x16x32_bf16 v[4:7], v[58:61], v[50:53], v[4:7]
	ds_read_b128 v[58:61], v57 offset:39296
	s_waitcnt lgkmcnt(0)
	v_mfma_f32_16x16x32_bf16 v[8:11], v[58:61], v[50:53], v[8:11]
	ds_read_b128 v[58:61], v57 offset:43648
	s_waitcnt lgkmcnt(0)
	v_mfma_f32_16x16x32_bf16 v[12:15], v[58:61], v[50:53], v[12:15]
	ds_read_b128 v[58:61], v57 offset:48000
	s_waitcnt lgkmcnt(0)
	v_mfma_f32_16x16x32_bf16 v[18:21], v[58:61], v[50:53], v[18:21]
	ds_read_b128 v[58:61], v57 offset:52352
	s_waitcnt lgkmcnt(0)
	v_mfma_f32_16x16x32_bf16 v[58:61], v[58:61], v[50:53], v[22:25]
	s_nop 2
	ds_read_b128 v[22:25], v57 offset:56704
	s_waitcnt lgkmcnt(0)
	v_mfma_f32_16x16x32_bf16 v[62:65], v[22:25], v[50:53], v[26:29]
	ds_read_b128 v[22:25], v57 offset:61056
	s_waitcnt lgkmcnt(0)
	v_mfma_f32_16x16x32_bf16 v[66:69], v[22:25], v[50:53], v[30:33]
	ds_read_b128 v[22:25], v57 offset:65408
	s_waitcnt lgkmcnt(0)
	v_mfma_f32_16x16x32_bf16 v[0:3], v[22:25], v[50:53], v[0:3]
	ds_read_b128 v[50:53], v38 offset:192
	ds_read_b128 v[22:25], v57 offset:35008
	s_waitcnt lgkmcnt(0)
	v_mfma_f32_16x16x32_bf16 v[30:33], v[22:25], v[50:53], v[4:7]
	s_nop 2
	ds_read_b128 v[4:7], v57 offset:39360
	s_waitcnt lgkmcnt(0)
	v_mfma_f32_16x16x32_bf16 v[26:29], v[4:7], v[50:53], v[8:11]
	ds_read_b128 v[4:7], v57 offset:43712
	s_waitcnt lgkmcnt(0)
	v_mfma_f32_16x16x32_bf16 v[22:25], v[4:7], v[50:53], v[12:15]
	ds_read_b128 v[4:7], v57 offset:48064
	s_waitcnt lgkmcnt(0)
	v_mfma_f32_16x16x32_bf16 v[18:21], v[4:7], v[50:53], v[18:21]
	ds_read_b128 v[4:7], v57 offset:52416
	s_waitcnt lgkmcnt(0)
	v_mfma_f32_16x16x32_bf16 v[12:15], v[4:7], v[50:53], v[58:61]
	ds_read_b128 v[4:7], v57 offset:56768
	s_nop 1
	ds_read_b128 v[58:61], v57 offset:65472
	s_waitcnt lgkmcnt(1)
	v_mfma_f32_16x16x32_bf16 v[8:11], v[4:7], v[50:53], v[62:65]
	ds_read_b128 v[4:7], v57 offset:61120
	s_mov_b32 s4, 0
	s_ashr_i32 s5, s4, 31
	s_lshl_b64 s[4:5], s[4:5], 3
	s_add_u32 s4, s0, s4
	s_addc_u32 s5, s1, s5
	s_load_dwordx2 s[4:5], s[4:5], 0x50
	s_waitcnt lgkmcnt(0)
	v_mfma_f32_16x16x32_bf16 v[4:7], v[4:7], v[50:53], v[66:69]
	v_mfma_f32_16x16x32_bf16 v[0:3], v[58:61], v[50:53], v[0:3]
	v_lshl_add_u64 v[50:51], s[4:5], 0, v[44:45]
	v_lshl_add_u64 v[50:51], v[50:51], 0, s[42:43]
	v_mov_b32_e32 v58, v224
	v_lshl_add_u64 v[50:51], s[90:91], 0, v[48:49]
	v_add_co_u32_e32 v50, vcc, s86, v50
	v_lshl_add_u64 v[52:53], s[90:91], 0, v[46:47]
	s_nop 0
	v_addc_co_u32_e32 v51, vcc, 0, v51, vcc
	v_mov_b64_e32 v[54:55], v[208:209]
	s_add_u32 s42, s42, 0x200
	s_addc_u32 s43, s43, 0
	s_add_u32 s90, s90, 0x100
	s_addc_u32 s91, s91, 0
	s_cmpk_eq_i32 s42, 0x800
	v_add_f32_e32 v30, v30, v58
	v_add_f32_e32 v31, v31, v58
	v_add_f32_e32 v26, v26, v58
	v_add_f32_e32 v27, v27, v58
	v_add_f32_e32 v22, v22, v58
	v_add_f32_e32 v23, v23, v58
	v_add_f32_e32 v18, v18, v58
	s_waitcnt lgkmcnt(0)
	v_lshlrev_b32_e32 v59, 16, v54
	v_mul_f32_e32 v60, 0x3d372713, v59
	v_mul_f32_e32 v60, v60, v59
	v_fma_f32 v60, v60, v59, v59
	v_mul_f32_e32 v60, 0xbfcc422a, v60
	v_mul_f32_e32 v60, 0x3fb8aa3b, v60
	v_exp_f32_e32 v60, v60
	v_and_b32_e32 v54, 0xffff0000, v54
	v_add_f32_e32 v19, v19, v58
	v_add_f32_e32 v12, v12, v58
	v_add_f32_e32 v60, 1.0, v60
	v_rcp_f32_e32 v60, v60
	v_add_f32_e32 v13, v13, v58
	v_add_f32_e32 v8, v8, v58
	v_add_f32_e32 v9, v9, v58
	v_mul_f32_e32 v59, v60, v59
	v_mul_f32_e32 v30, v30, v59
	v_mul_f32_e32 v59, 0x3d372713, v54
	v_mul_f32_e32 v59, v59, v54
	v_fma_f32 v59, v59, v54, v54
	v_mul_f32_e32 v59, 0xbfcc422a, v59
	v_mul_f32_e32 v59, 0x3fb8aa3b, v59
	v_exp_f32_e32 v59, v59
	v_add_f32_e32 v4, v4, v58
	v_add_f32_e32 v5, v5, v58
	v_add_f32_e32 v0, v0, v58
	v_add_f32_e32 v59, 1.0, v59
	v_rcp_f32_e32 v59, v59
	v_add_f32_e32 v1, v1, v58
	v_mul_f32_e32 v54, v59, v54
	v_mul_f32_e32 v31, v31, v54
	v_cvt_pk_bf16_f32 v54, v30, v31
	v_lshlrev_b32_e32 v31, 16, v55
	v_add_f32_e32 v30, v32, v58
	v_mul_f32_e32 v32, 0x3d372713, v31
	v_mul_f32_e32 v32, v32, v31
	v_fma_f32 v32, v32, v31, v31
	v_mul_f32_e32 v32, 0xbfcc422a, v32
	v_mul_f32_e32 v32, 0x3fb8aa3b, v32
	v_exp_f32_e32 v32, v32
	s_nop 0
	v_add_f32_e32 v32, 1.0, v32
	v_rcp_f32_e32 v32, v32
	s_nop 0
	v_mul_f32_e32 v31, v32, v31
	v_and_b32_e32 v32, 0xffff0000, v55
	v_mul_f32_e32 v30, v30, v31
	v_add_f32_e32 v31, v33, v58
	v_mul_f32_e32 v33, 0x3d372713, v32
	v_mul_f32_e32 v33, v33, v32
	v_fma_f32 v33, v33, v32, v32
	v_mul_f32_e32 v33, 0xbfcc422a, v33
	v_mul_f32_e32 v33, 0x3fb8aa3b, v33
	v_exp_f32_e32 v33, v33
	s_nop 0
	v_add_f32_e32 v33, 1.0, v33
	v_rcp_f32_e32 v33, v33
	s_nop 0
	v_mul_f32_e32 v32, v33, v32
	v_mul_f32_e32 v31, v31, v32
	v_cvt_pk_bf16_f32 v55, v30, v31
	v_add_co_u32_e32 v30, vcc, s2, v52
	s_nop 1
	v_addc_co_u32_e32 v31, vcc, 0, v53, vcc
	flat_store_dwordx2 v[30:31], v[54:55]
	v_mov_b64_e32 v[32:33], v[210:211]
	s_waitcnt lgkmcnt(0)
	v_lshlrev_b32_e32 v52, 16, v32
	v_mul_f32_e32 v53, 0x3d372713, v52
	v_mul_f32_e32 v53, v53, v52
	v_fma_f32 v53, v53, v52, v52
	v_mul_f32_e32 v53, 0xbfcc422a, v53
	v_mul_f32_e32 v53, 0x3fb8aa3b, v53
	v_exp_f32_e32 v53, v53
	v_and_b32_e32 v32, 0xffff0000, v32
	v_add_f32_e32 v53, 1.0, v53
	v_rcp_f32_e32 v53, v53
	s_nop 0
	v_mul_f32_e32 v52, v53, v52
	v_mul_f32_e32 v26, v26, v52
	v_mul_f32_e32 v52, 0x3d372713, v32
	v_mul_f32_e32 v52, v52, v32
	v_fma_f32 v52, v52, v32, v32
	v_mul_f32_e32 v52, 0xbfcc422a, v52
	v_mul_f32_e32 v52, 0x3fb8aa3b, v52
	v_exp_f32_e32 v52, v52
	s_nop 0
	v_add_f32_e32 v52, 1.0, v52
	v_rcp_f32_e32 v52, v52
	s_nop 0
	v_mul_f32_e32 v32, v52, v32
	v_mul_f32_e32 v27, v27, v32
	v_cvt_pk_bf16_f32 v26, v26, v27
	v_add_f32_e32 v27, v28, v58
	v_lshlrev_b32_e32 v28, 16, v33
	v_mul_f32_e32 v32, 0x3d372713, v28
	v_mul_f32_e32 v32, v32, v28
	v_fma_f32 v32, v32, v28, v28
	v_mul_f32_e32 v32, 0xbfcc422a, v32
	v_mul_f32_e32 v32, 0x3fb8aa3b, v32
	v_exp_f32_e32 v32, v32
	s_nop 0
	v_add_f32_e32 v32, 1.0, v32
	v_rcp_f32_e32 v32, v32
	s_nop 0
	v_mul_f32_e32 v28, v32, v28
	v_mul_f32_e32 v27, v27, v28
	v_add_f32_e32 v28, v29, v58
	v_and_b32_e32 v29, 0xffff0000, v33
	v_mul_f32_e32 v32, 0x3d372713, v29
	v_mul_f32_e32 v32, v32, v29
	v_fma_f32 v32, v32, v29, v29
	v_mul_f32_e32 v32, 0xbfcc422a, v32
	v_mul_f32_e32 v32, 0x3fb8aa3b, v32
	v_exp_f32_e32 v32, v32
	s_nop 0
	v_add_f32_e32 v32, 1.0, v32
	v_rcp_f32_e32 v32, v32
	s_nop 0
	v_mul_f32_e32 v29, v32, v29
	v_mul_f32_e32 v28, v28, v29
	v_cvt_pk_bf16_f32 v27, v27, v28
	flat_store_dwordx2 v[30:31], v[26:27] offset:32
	v_mov_b64_e32 v[26:27], v[212:213]
	s_waitcnt lgkmcnt(0)
	v_lshlrev_b32_e32 v28, 16, v26
	v_mul_f32_e32 v29, 0x3d372713, v28
	v_mul_f32_e32 v29, v29, v28
	v_fma_f32 v29, v29, v28, v28
	v_mul_f32_e32 v29, 0xbfcc422a, v29
	v_mul_f32_e32 v29, 0x3fb8aa3b, v29
	v_exp_f32_e32 v29, v29
	v_and_b32_e32 v26, 0xffff0000, v26
	v_add_f32_e32 v29, 1.0, v29
	v_rcp_f32_e32 v29, v29
	s_nop 0
	v_mul_f32_e32 v28, v29, v28
	v_mul_f32_e32 v22, v22, v28
	v_mul_f32_e32 v28, 0x3d372713, v26
	v_mul_f32_e32 v28, v28, v26
	v_fma_f32 v28, v28, v26, v26
	v_mul_f32_e32 v28, 0xbfcc422a, v28
	v_mul_f32_e32 v28, 0x3fb8aa3b, v28
	v_exp_f32_e32 v28, v28
	s_nop 0
	v_add_f32_e32 v28, 1.0, v28
	v_rcp_f32_e32 v28, v28
	s_nop 0
	v_mul_f32_e32 v26, v28, v26
	v_mul_f32_e32 v23, v23, v26
	v_cvt_pk_bf16_f32 v22, v22, v23
	v_add_f32_e32 v23, v24, v58
	v_lshlrev_b32_e32 v24, 16, v27
	v_mul_f32_e32 v26, 0x3d372713, v24
	v_mul_f32_e32 v26, v26, v24
	v_fma_f32 v26, v26, v24, v24
	v_mul_f32_e32 v26, 0xbfcc422a, v26
	v_mul_f32_e32 v26, 0x3fb8aa3b, v26
	v_exp_f32_e32 v26, v26
	s_nop 0
	v_add_f32_e32 v26, 1.0, v26
	v_rcp_f32_e32 v26, v26
	s_nop 0
	v_mul_f32_e32 v24, v26, v24
	v_mul_f32_e32 v23, v23, v24
	v_add_f32_e32 v24, v25, v58
	v_and_b32_e32 v25, 0xffff0000, v27
	v_mul_f32_e32 v26, 0x3d372713, v25
	v_mul_f32_e32 v26, v26, v25
	v_fma_f32 v26, v26, v25, v25
	v_mul_f32_e32 v26, 0xbfcc422a, v26
	v_mul_f32_e32 v26, 0x3fb8aa3b, v26
	v_exp_f32_e32 v26, v26
	s_nop 0
	v_add_f32_e32 v26, 1.0, v26
	v_rcp_f32_e32 v26, v26
	s_nop 0
	v_mul_f32_e32 v25, v26, v25
	v_mul_f32_e32 v24, v24, v25
	v_cvt_pk_bf16_f32 v23, v23, v24
	flat_store_dwordx2 v[30:31], v[22:23] offset:64
	v_mov_b64_e32 v[22:23], v[214:215]
	s_waitcnt lgkmcnt(0)
	v_lshlrev_b32_e32 v24, 16, v22
	v_mul_f32_e32 v25, 0x3d372713, v24
	v_mul_f32_e32 v25, v25, v24
	v_fma_f32 v25, v25, v24, v24
	v_mul_f32_e32 v25, 0xbfcc422a, v25
	v_mul_f32_e32 v25, 0x3fb8aa3b, v25
	v_exp_f32_e32 v25, v25
	v_and_b32_e32 v22, 0xffff0000, v22
	v_add_f32_e32 v25, 1.0, v25
	v_rcp_f32_e32 v25, v25
	s_nop 0
	v_mul_f32_e32 v24, v25, v24
	v_mul_f32_e32 v18, v18, v24
	v_mul_f32_e32 v24, 0x3d372713, v22
	v_mul_f32_e32 v24, v24, v22
	v_fma_f32 v24, v24, v22, v22
	v_mul_f32_e32 v24, 0xbfcc422a, v24
	v_mul_f32_e32 v24, 0x3fb8aa3b, v24
	v_exp_f32_e32 v24, v24
	s_nop 0
	v_add_f32_e32 v24, 1.0, v24
	v_rcp_f32_e32 v24, v24
	s_nop 0
	v_mul_f32_e32 v22, v24, v22
	v_mul_f32_e32 v19, v19, v22
	v_cvt_pk_bf16_f32 v18, v18, v19
	v_add_f32_e32 v19, v20, v58
	v_lshlrev_b32_e32 v20, 16, v23
	v_mul_f32_e32 v22, 0x3d372713, v20
	v_mul_f32_e32 v22, v22, v20
	v_fma_f32 v22, v22, v20, v20
	v_mul_f32_e32 v22, 0xbfcc422a, v22
	v_mul_f32_e32 v22, 0x3fb8aa3b, v22
	v_exp_f32_e32 v22, v22
	s_nop 0
	v_add_f32_e32 v22, 1.0, v22
	v_rcp_f32_e32 v22, v22
	s_nop 0
	v_mul_f32_e32 v20, v22, v20
	v_mul_f32_e32 v19, v19, v20
	v_add_f32_e32 v20, v21, v58
	v_and_b32_e32 v21, 0xffff0000, v23
	v_mul_f32_e32 v22, 0x3d372713, v21
	v_mul_f32_e32 v22, v22, v21
	v_fma_f32 v22, v22, v21, v21
	v_mul_f32_e32 v22, 0xbfcc422a, v22
	v_mul_f32_e32 v22, 0x3fb8aa3b, v22
	v_exp_f32_e32 v22, v22
	s_nop 0
	v_add_f32_e32 v22, 1.0, v22
	v_rcp_f32_e32 v22, v22
	s_nop 0
	v_mul_f32_e32 v21, v22, v21
	v_mul_f32_e32 v20, v20, v21
	v_cvt_pk_bf16_f32 v19, v19, v20
	flat_store_dwordx2 v[30:31], v[18:19] offset:96
	v_mov_b64_e32 v[18:19], v[216:217]
	s_waitcnt lgkmcnt(0)
	v_lshlrev_b32_e32 v20, 16, v18
	v_mul_f32_e32 v21, 0x3d372713, v20
	v_mul_f32_e32 v21, v21, v20
	v_fma_f32 v21, v21, v20, v20
	v_mul_f32_e32 v21, 0xbfcc422a, v21
	v_mul_f32_e32 v21, 0x3fb8aa3b, v21
	v_exp_f32_e32 v21, v21
	v_and_b32_e32 v18, 0xffff0000, v18
	v_add_f32_e32 v21, 1.0, v21
	v_rcp_f32_e32 v21, v21
	s_nop 0
	v_mul_f32_e32 v20, v21, v20
	v_mul_f32_e32 v12, v12, v20
	v_mul_f32_e32 v20, 0x3d372713, v18
	v_mul_f32_e32 v20, v20, v18
	v_fma_f32 v20, v20, v18, v18
	v_mul_f32_e32 v20, 0xbfcc422a, v20
	v_mul_f32_e32 v20, 0x3fb8aa3b, v20
	v_exp_f32_e32 v20, v20
	s_nop 0
	v_add_f32_e32 v20, 1.0, v20
	v_rcp_f32_e32 v20, v20
	s_nop 0
	v_mul_f32_e32 v18, v20, v18
	v_mul_f32_e32 v13, v13, v18
	v_cvt_pk_bf16_f32 v12, v12, v13
	v_add_f32_e32 v13, v14, v58
	v_lshlrev_b32_e32 v14, 16, v19
	v_mul_f32_e32 v18, 0x3d372713, v14
	v_mul_f32_e32 v18, v18, v14
	v_fma_f32 v18, v18, v14, v14
	v_mul_f32_e32 v18, 0xbfcc422a, v18
	v_mul_f32_e32 v18, 0x3fb8aa3b, v18
	v_exp_f32_e32 v18, v18
	s_nop 0
	v_add_f32_e32 v18, 1.0, v18
	v_rcp_f32_e32 v18, v18
	s_nop 0
	v_mul_f32_e32 v14, v18, v14
	v_mul_f32_e32 v13, v13, v14
	v_add_f32_e32 v14, v15, v58
	v_and_b32_e32 v15, 0xffff0000, v19
	v_mul_f32_e32 v18, 0x3d372713, v15
	v_mul_f32_e32 v18, v18, v15
	v_fma_f32 v18, v18, v15, v15
	v_mul_f32_e32 v18, 0xbfcc422a, v18
	v_mul_f32_e32 v18, 0x3fb8aa3b, v18
	v_exp_f32_e32 v18, v18
	s_nop 0
	v_add_f32_e32 v18, 1.0, v18
	v_rcp_f32_e32 v18, v18
	s_nop 0
	v_mul_f32_e32 v15, v18, v15
	v_mul_f32_e32 v14, v14, v15
	v_cvt_pk_bf16_f32 v13, v13, v14
	flat_store_dwordx2 v[30:31], v[12:13] offset:128
	v_mov_b64_e32 v[12:13], v[218:219]
	s_waitcnt lgkmcnt(0)
	v_lshlrev_b32_e32 v14, 16, v12
	v_mul_f32_e32 v15, 0x3d372713, v14
	v_mul_f32_e32 v15, v15, v14
	v_fma_f32 v15, v15, v14, v14
	v_mul_f32_e32 v15, 0xbfcc422a, v15
	v_mul_f32_e32 v15, 0x3fb8aa3b, v15
	v_exp_f32_e32 v15, v15
	v_and_b32_e32 v12, 0xffff0000, v12
	v_add_f32_e32 v15, 1.0, v15
	v_rcp_f32_e32 v15, v15
	s_nop 0
	v_mul_f32_e32 v14, v15, v14
	v_mul_f32_e32 v8, v8, v14
	v_mul_f32_e32 v14, 0x3d372713, v12
	v_mul_f32_e32 v14, v14, v12
	v_fma_f32 v14, v14, v12, v12
	v_mul_f32_e32 v14, 0xbfcc422a, v14
	v_mul_f32_e32 v14, 0x3fb8aa3b, v14
	v_exp_f32_e32 v14, v14
	s_nop 0
	v_add_f32_e32 v14, 1.0, v14
	v_rcp_f32_e32 v14, v14
	s_nop 0
	v_mul_f32_e32 v12, v14, v12
	v_mul_f32_e32 v9, v9, v12
	v_cvt_pk_bf16_f32 v8, v8, v9
	v_add_f32_e32 v9, v10, v58
	v_lshlrev_b32_e32 v10, 16, v13
	v_mul_f32_e32 v12, 0x3d372713, v10
	v_mul_f32_e32 v12, v12, v10
	v_fma_f32 v12, v12, v10, v10
	v_mul_f32_e32 v12, 0xbfcc422a, v12
	v_mul_f32_e32 v12, 0x3fb8aa3b, v12
	v_exp_f32_e32 v12, v12
	s_nop 0
	v_add_f32_e32 v12, 1.0, v12
	v_rcp_f32_e32 v12, v12
	s_nop 0
	v_mul_f32_e32 v10, v12, v10
	v_mul_f32_e32 v9, v9, v10
	v_add_f32_e32 v10, v11, v58
	v_and_b32_e32 v11, 0xffff0000, v13
	v_mul_f32_e32 v12, 0x3d372713, v11
	v_mul_f32_e32 v12, v12, v11
	v_fma_f32 v12, v12, v11, v11
	v_mul_f32_e32 v12, 0xbfcc422a, v12
	v_mul_f32_e32 v12, 0x3fb8aa3b, v12
	v_exp_f32_e32 v12, v12
	s_nop 0
	v_add_f32_e32 v12, 1.0, v12
	v_rcp_f32_e32 v12, v12
	s_nop 0
	v_mul_f32_e32 v11, v12, v11
	v_mul_f32_e32 v10, v10, v11
	v_cvt_pk_bf16_f32 v9, v9, v10
	flat_store_dwordx2 v[30:31], v[8:9] offset:160
	v_mov_b64_e32 v[8:9], v[220:221]
	s_waitcnt lgkmcnt(0)
	v_lshlrev_b32_e32 v10, 16, v8
	v_mul_f32_e32 v11, 0x3d372713, v10
	v_mul_f32_e32 v11, v11, v10
	v_fma_f32 v11, v11, v10, v10
	v_mul_f32_e32 v11, 0xbfcc422a, v11
	v_mul_f32_e32 v11, 0x3fb8aa3b, v11
	v_exp_f32_e32 v11, v11
	v_and_b32_e32 v8, 0xffff0000, v8
	v_add_f32_e32 v11, 1.0, v11
	v_rcp_f32_e32 v11, v11
	s_nop 0
	v_mul_f32_e32 v10, v11, v10
	v_mul_f32_e32 v4, v4, v10
	v_mul_f32_e32 v10, 0x3d372713, v8
	v_mul_f32_e32 v10, v10, v8
	v_fma_f32 v10, v10, v8, v8
	v_mul_f32_e32 v10, 0xbfcc422a, v10
	v_mul_f32_e32 v10, 0x3fb8aa3b, v10
	v_exp_f32_e32 v10, v10
	s_nop 0
	v_add_f32_e32 v10, 1.0, v10
	v_rcp_f32_e32 v10, v10
	s_nop 0
	v_mul_f32_e32 v8, v10, v8
	v_mul_f32_e32 v5, v5, v8
	v_cvt_pk_bf16_f32 v4, v4, v5
	v_add_f32_e32 v5, v6, v58
	v_lshlrev_b32_e32 v6, 16, v9
	v_mul_f32_e32 v8, 0x3d372713, v6
	v_mul_f32_e32 v8, v8, v6
	v_fma_f32 v8, v8, v6, v6
	v_mul_f32_e32 v8, 0xbfcc422a, v8
	v_mul_f32_e32 v8, 0x3fb8aa3b, v8
	v_exp_f32_e32 v8, v8
	s_nop 0
	v_add_f32_e32 v8, 1.0, v8
	v_rcp_f32_e32 v8, v8
	s_nop 0
	v_mul_f32_e32 v6, v8, v6
	v_mul_f32_e32 v5, v5, v6
	v_add_f32_e32 v6, v7, v58
	v_and_b32_e32 v7, 0xffff0000, v9
	v_mul_f32_e32 v8, 0x3d372713, v7
	v_mul_f32_e32 v8, v8, v7
	v_fma_f32 v8, v8, v7, v7
	v_mul_f32_e32 v8, 0xbfcc422a, v8
	v_mul_f32_e32 v8, 0x3fb8aa3b, v8
	v_exp_f32_e32 v8, v8
	s_nop 0
	v_add_f32_e32 v8, 1.0, v8
	v_rcp_f32_e32 v8, v8
	s_nop 0
	v_mul_f32_e32 v7, v8, v7
	v_mul_f32_e32 v6, v6, v7
	v_cvt_pk_bf16_f32 v5, v5, v6
	flat_store_dwordx2 v[30:31], v[4:5] offset:192
	v_mov_b64_e32 v[4:5], v[222:223]
	s_waitcnt lgkmcnt(0)
	v_lshlrev_b32_e32 v6, 16, v4
	v_mul_f32_e32 v7, 0x3d372713, v6
	v_mul_f32_e32 v7, v7, v6
	v_fma_f32 v7, v7, v6, v6
	v_mul_f32_e32 v7, 0xbfcc422a, v7
	v_mul_f32_e32 v7, 0x3fb8aa3b, v7
	v_exp_f32_e32 v7, v7
	v_and_b32_e32 v4, 0xffff0000, v4
	v_add_f32_e32 v7, 1.0, v7
	v_rcp_f32_e32 v7, v7
	s_nop 0
	v_mul_f32_e32 v6, v7, v6
	v_mul_f32_e32 v0, v0, v6
	v_mul_f32_e32 v6, 0x3d372713, v4
	v_mul_f32_e32 v6, v6, v4
	v_fma_f32 v6, v6, v4, v4
	v_mul_f32_e32 v6, 0xbfcc422a, v6
	v_mul_f32_e32 v6, 0x3fb8aa3b, v6
	v_exp_f32_e32 v6, v6
	s_nop 0
	v_add_f32_e32 v6, 1.0, v6
	v_rcp_f32_e32 v6, v6
	s_nop 0
	v_mul_f32_e32 v4, v6, v4
	v_mul_f32_e32 v1, v1, v4
	v_cvt_pk_bf16_f32 v0, v0, v1
	v_add_f32_e32 v1, v2, v58
	v_lshlrev_b32_e32 v2, 16, v5
	v_mul_f32_e32 v4, 0x3d372713, v2
	v_mul_f32_e32 v4, v4, v2
	v_fma_f32 v4, v4, v2, v2
	v_mul_f32_e32 v4, 0xbfcc422a, v4
	v_mul_f32_e32 v4, 0x3fb8aa3b, v4
	v_exp_f32_e32 v4, v4
	s_nop 0
	v_add_f32_e32 v4, 1.0, v4
	v_rcp_f32_e32 v4, v4
	s_nop 0
	v_mul_f32_e32 v2, v4, v2
	v_mul_f32_e32 v1, v1, v2
	v_add_f32_e32 v2, v3, v58
	v_and_b32_e32 v3, 0xffff0000, v5
	v_mul_f32_e32 v4, 0x3d372713, v3
	v_mul_f32_e32 v4, v4, v3
	v_fma_f32 v4, v4, v3, v3
	v_mul_f32_e32 v4, 0xbfcc422a, v4
	v_mul_f32_e32 v4, 0x3fb8aa3b, v4
	v_exp_f32_e32 v4, v4
	s_nop 0
	v_add_f32_e32 v4, 1.0, v4
	v_rcp_f32_e32 v4, v4
	s_nop 0
	v_mul_f32_e32 v3, v4, v3
	v_mul_f32_e32 v2, v2, v3
	v_cvt_pk_bf16_f32 v1, v1, v2
	flat_store_dwordx2 v[30:31], v[0:1] offset:224
	s_waitcnt lgkmcnt(0)
	s_barrier
	s_cbranch_scc0 .LBB0_680
